# MoBA far steps whose key range lies in one distance bucket skip the per-element bias select
# speedup vs baseline: 1.0035x; 1.0035x over previous
; __device__ __forceinline__ float pair_max(float v) { auto r = __builtin_amdgcn_permlane32_swap(__float_as_uint(v), __float_as_uint(v), false, false); return fmaxf(__uint_as_float(r[0]), __uint_as_float(r[1])); }
; __device__ __forceinline__ float pair_sum(float v) { auto r = __builtin_amdgcn_permlane32_swap(__float_as_uint(v), __float_as_uint(v), false, false); return __uint_as_float(r[0]) + __uint_as_float(r[1]); }
; template <bool CAUSAL> __device__ __forceinline__ void moba_span(lbyte* kbuf, lbyte* vbuf, const bf16* Kh, const bf16* Vh, int kpos0, int nsub, const s16x8* qf, int tq, bool valid, int qlo, int qhi, ...
;     ...
;         if (!CAUSAL && bmax - bmin <= 1) {
;             const float t0 = tab[bmin], t1 = tab[bmax]; const int th1 = thr[bmax];
;             float mxr = s[0][0];
; #pragma unroll
;             for (int r = 1; r < 16; ++r) mxr = fmaxf(mxr, s[0][r]);
;             mxr = pair_max(mxr);
;             const float cL = valid ? 0.125f * LOG2E : 0.f, bL = valid ? t0 : -INFINITY, mx = valid ? mxr * (0.125f * LOG2E) + fmaxf(t0, t1) : -INFINITY;
;             const bool grow = mx > m + 8.0f; const float mn = grow ? mx : m, off = bL - mn, offB = off + (t1 - t0);
;             if (__any(grow)) { const float alpha = __builtin_amdgcn_exp2f(m - mn); l *= alpha; o[0] = o[0] * alpha; o[1] = o[1] * alpha; }
;             m = mn;
;             const int x1 = (bmax > bmin) ? tq - key0 - th1 : -0x40000000; f32x2_t sum2 = {0.f, 0.f};
; #pragma unroll
;             for (int r = 0; r < 16; r += 2) { const int kk = kkrow(r, h);
;                 const f32x2_t ob = {x1 >= kk ? offB : off, x1 >= kk + 1 ? offB : off}; f32x2_t v = {s[0][r], s[0][r + 1]}; v = v * (f32x2_t){cL, cL} + ob;
;                 const float e0 = __builtin_amdgcn_exp2f(v.x), e1 = __builtin_amdgcn_exp2f(v.y); s[0][r] = e0; s[0][r + 1] = e1; sum2 += (f32x2_t){e0, e1}; }
;             l += pair_sum(sum2.x + sum2.y);
.LBB0_674:
	s_cmp_gt_u32 s17, s15
	s_waitcnt lgkmcnt(0)
	s_cbranch_scc0 .Lmoba_fast
	v_sub_u32_e32 v34, s11, v34
	v_cndmask_b32_e64 v0, v238, v35, s[8:9]
	v_add_u32_e32 v34, v34, v235
	s_cselect_b64 vcc, -1, 0
	v_sub_f32_e32 v0, v0, v194
	v_sub_f32_e32 v35, v36, v35
	v_cndmask_b32_e32 v39, -2.0, v34, vcc
	v_add_f32_e32 v38, v35, v0
	v_cmp_lt_i32_e32 vcc, v39, v241
	v_mov_b32_e32 v162, v195
	s_nop 0
	v_cndmask_b32_e32 v34, v38, v0, vcc
	v_cmp_gt_i32_e32 vcc, v39, v241
	s_nop 1
	v_cndmask_b32_e32 v35, v0, v38, vcc
	v_pk_fma_f32 v[34:35], v[196:197], v[66:67], v[34:35]
	v_cmp_lt_i32_e32 vcc, v39, v243
	v_exp_f32_e32 v82, v34
	v_exp_f32_e32 v83, v35
	v_cndmask_b32_e32 v34, v38, v0, vcc
	v_cmp_gt_i32_e32 vcc, v39, v243
	s_nop 1
	v_cndmask_b32_e32 v35, v0, v38, vcc
	v_pk_fma_f32 v[34:35], v[196:197], v[68:69], v[34:35]
	v_cmp_lt_i32_e32 vcc, v39, v244
	v_exp_f32_e32 v84, v34
	v_exp_f32_e32 v85, v35
	v_cndmask_b32_e32 v34, v38, v0, vcc
	v_cmp_gt_i32_e32 vcc, v39, v244
	s_nop 1
	v_cndmask_b32_e32 v35, v0, v38, vcc
	v_pk_fma_f32 v[34:35], v[196:197], v[70:71], v[34:35]
	v_cmp_lt_i32_e32 vcc, v39, v245
	v_exp_f32_e32 v86, v34
	v_exp_f32_e32 v87, v35
	v_cndmask_b32_e32 v34, v38, v0, vcc
	v_cmp_gt_i32_e32 vcc, v39, v245
	s_nop 1
	v_cndmask_b32_e32 v35, v0, v38, vcc
	v_cmp_lt_i32_e32 vcc, v39, v246
	v_pk_fma_f32 v[34:35], v[196:197], v[72:73], v[34:35]
	s_nop 0
	v_cndmask_b32_e32 v36, v38, v0, vcc
	v_cmp_gt_i32_e32 vcc, v39, v246
	v_exp_f32_e32 v88, v34
	v_exp_f32_e32 v89, v35
	v_cndmask_b32_e32 v37, v0, v38, vcc
	v_pk_fma_f32 v[36:37], v[196:197], v[74:75], v[36:37]
	v_cmp_lt_i32_e32 vcc, v39, v247
	v_exp_f32_e32 v90, v36
	v_exp_f32_e32 v91, v37
	v_cndmask_b32_e32 v36, v38, v0, vcc
	v_cmp_gt_i32_e32 vcc, v39, v247
	v_pk_add_f32 v[34:35], v[82:83], 0 op_sel_hi:[1,0]
	s_nop 0
	v_cndmask_b32_e32 v37, v0, v38, vcc
	v_pk_fma_f32 v[36:37], v[196:197], v[76:77], v[36:37]
	v_cmp_lt_i32_e32 vcc, v39, v248
	v_exp_f32_e32 v92, v36
	v_exp_f32_e32 v93, v37
	v_cndmask_b32_e32 v36, v38, v0, vcc
	v_cmp_gt_i32_e32 vcc, v39, v248
	v_pk_add_f32 v[34:35], v[84:85], v[34:35]
	s_nop 0
	v_cndmask_b32_e32 v37, v0, v38, vcc
	v_pk_fma_f32 v[36:37], v[196:197], v[78:79], v[36:37]
	v_cmp_lt_i32_e32 vcc, v39, v249
	v_exp_f32_e32 v94, v36
	v_exp_f32_e32 v95, v37
	v_cndmask_b32_e32 v36, v38, v0, vcc
	v_cmp_gt_i32_e32 vcc, v39, v249
	v_pk_add_f32 v[34:35], v[86:87], v[34:35]
	s_nop 0
	v_cndmask_b32_e32 v37, v0, v38, vcc
	v_pk_fma_f32 v[36:37], v[196:197], v[80:81], v[36:37]
	v_pk_add_f32 v[34:35], v[88:89], v[34:35]
	v_exp_f32_e32 v96, v36
	v_exp_f32_e32 v97, v37
	v_pk_add_f32 v[34:35], v[90:91], v[34:35]
	s_nop 0
	v_pk_add_f32 v[34:35], v[92:93], v[34:35]
	s_nop 0
	v_pk_add_f32 v[34:35], v[94:95], v[34:35]
	s_nop 0
	v_pk_add_f32 v[34:35], v[96:97], v[34:35]
	s_nop 0
	v_pk_add_f32 v[230:231], v[34:35], v[34:35] op_sel:[0,1] op_sel_hi:[1,0]
	v_mov_b32_e32 v163, v230
	s_nop 1
	v_permlane32_swap_b32_e32 v230, v163

; __device__ __forceinline__ float pair_sum(float v) { auto r = __builtin_amdgcn_permlane32_swap(__float_as_uint(v), __float_as_uint(v), false, false); return __uint_as_float(r[0]) + __uint_as_float(r[1]); }
; template <bool CAUSAL> __device__ __forceinline__ void moba_span(lbyte* kbuf, lbyte* vbuf, const bf16* Kh, const bf16* Vh, int kpos0, int nsub, const s16x8* qf, int tq, bool valid, int qlo, int qhi, ...
;     ...
;             const float cL = valid ? 0.125f * LOG2E : 0.f, bL = valid ? t0 : -INFINITY, mx = valid ? mxr * (0.125f * LOG2E) + fmaxf(t0, t1) : -INFINITY;
;             const bool grow = mx > m + 8.0f; const float mn = grow ? mx : m, off = bL - mn, offB = off + (t1 - t0);
;             if (__any(grow)) { const float alpha = __builtin_amdgcn_exp2f(m - mn); l *= alpha; o[0] = o[0] * alpha; o[1] = o[1] * alpha; }
;             m = mn;
;             const int x1 = (bmax > bmin) ? tq - key0 - th1 : -0x40000000; f32x2_t sum2 = {0.f, 0.f};
; #pragma unroll
;             for (int r = 0; r < 16; r += 2) { const int kk = kkrow(r, h);
;                 const f32x2_t ob = {x1 >= kk ? offB : off, x1 >= kk + 1 ? offB : off}; f32x2_t v = {s[0][r], s[0][r + 1]}; v = v * (f32x2_t){cL, cL} + ob;
;                 const float e0 = __builtin_amdgcn_exp2f(v.x), e1 = __builtin_amdgcn_exp2f(v.y); s[0][r] = e0; s[0][r + 1] = e1; sum2 += (f32x2_t){e0, e1}; }
;             l += pair_sum(sum2.x + sum2.y);
.Lmoba_fast:
	v_cndmask_b32_e64 v0, v238, v35, s[8:9]
	v_mov_b32_e32 v162, v195
	v_sub_f32_e32 v0, v0, v194
	v_pk_fma_f32 v[34:35], v[196:197], v[66:67], v[0:1] op_sel_hi:[1,1,0]
	v_pk_fma_f32 v[36:37], v[196:197], v[68:69], v[0:1] op_sel_hi:[1,1,0]
	v_pk_fma_f32 v[38:39], v[196:197], v[70:71], v[0:1] op_sel_hi:[1,1,0]
	v_pk_fma_f32 v[40:41], v[196:197], v[72:73], v[0:1] op_sel_hi:[1,1,0]
	v_pk_fma_f32 v[42:43], v[196:197], v[74:75], v[0:1] op_sel_hi:[1,1,0]
	v_pk_fma_f32 v[44:45], v[196:197], v[76:77], v[0:1] op_sel_hi:[1,1,0]
	v_pk_fma_f32 v[46:47], v[196:197], v[78:79], v[0:1] op_sel_hi:[1,1,0]
	v_pk_fma_f32 v[48:49], v[196:197], v[80:81], v[0:1] op_sel_hi:[1,1,0]
	v_exp_f32_e32 v82, v34
	v_exp_f32_e32 v83, v35
	v_exp_f32_e32 v84, v36
	v_exp_f32_e32 v85, v37
	v_exp_f32_e32 v86, v38
	v_exp_f32_e32 v87, v39
	v_exp_f32_e32 v88, v40
	v_exp_f32_e32 v89, v41
	v_exp_f32_e32 v90, v42
	v_exp_f32_e32 v91, v43
	v_exp_f32_e32 v92, v44
	v_exp_f32_e32 v93, v45
	v_exp_f32_e32 v94, v46
	v_exp_f32_e32 v95, v47
	v_exp_f32_e32 v96, v48
	v_exp_f32_e32 v97, v49
	v_pk_add_f32 v[34:35], v[82:83], v[84:85]
	v_pk_add_f32 v[36:37], v[86:87], v[88:89]
	v_pk_add_f32 v[38:39], v[90:91], v[92:93]
	v_pk_add_f32 v[40:41], v[94:95], v[96:97]
	v_pk_add_f32 v[34:35], v[34:35], v[36:37]
	v_pk_add_f32 v[38:39], v[38:39], v[40:41]
	s_nop 0
	v_pk_add_f32 v[34:35], v[34:35], v[38:39]
	s_nop 0
	v_add_f32_e32 v230, v34, v35
	v_mov_b32_e32 v163, v230
	s_nop 1
	v_permlane32_swap_b32_e32 v230, v163
	s_branch .LBB0_675
